# attention local stage: nine per-load waits before the K LDS writes merged into three
# baseline (speedup 1.0000x reference)
; #define LAS __attribute__((address_space(3)))
; __device__ __forceinline__ int kswz(int key) { return ((key >> 1) & 1) | (((key >> 3) & 3) << 1); }
; __device__ __forceinline__ void phase_mixer(const Params& p, LAS unsigned char* lds, int l, bool with_ctx, int G, int tid, int wave, int lane, int rep_attn, int rep_pool) {
;     ...
; #pragma unroll
;             for (int ps = 0; ps < 9; ++ps) { const int key = ps * 64 + (tid >> 3), idx = ps * 512 + tid, d = idx / 72, ch = idx - d * 72;
;                 *(LAS u32x4*)(lds + AT_KL + key * 128 + ((((tid & 7) ^ kswz(key))) << 4)) = kreg[ps];
;                 *(LAS u32x4*)(lds + AT_VL + d * AT_VLP + ((ch ^ (d & 15)) << 4)) = vreg[ps]; }
.LBB0_301:
	v_sub_u32_e64 v24, s71, 4 clamp
	v_min_u32_e32 v26, 56, v24
	s_barrier
	s_waitcnt vmcnt(6)
	ds_write_b128 v111, v[216:219]
	ds_write_b128 v111, v[224:227] offset:8192
	ds_write_b128 v111, v[228:231] offset:16384
	s_waitcnt vmcnt(3)
	ds_write_b128 v111, v[190:193] offset:24576
	ds_write_b128 v111, v[194:197] offset:32768
	ds_write_b128 v111, v[198:201] offset:40960
	s_waitcnt vmcnt(0)
	ds_write_b128 v111, v[202:205] offset:49152
	ds_write_b128 v111, v[182:185] offset:57344
	ds_write_b128 v125, v[186:189]
	s_mov_b32 s80, 0x3a800000
	s_mov_b64 s[68:69], exec
	s_cmp_eq_u32 s61, s2
	s_cbranch_scc1 .Lrpb_load
	s_and_b32 s32, s3, 7
	s_cmp_eq_u32 s32, 0
	s_cbranch_scc1 .LBB0_296
